# conv: removed vmcnt(0) at sweep start that drained the just-issued order-1 filter prefetch
# speedup vs baseline: 1.0009x; 1.0009x over previous
; #define LAS __attribute__((address_space(3)))
; #define GATHER(dst, lagoff) do { unsigned _d[5]; ARAW(_d, lagoff); AFIN(dst, _d); } while (0)
; template <int NQ, int NB, int L>
; __device__ __forceinline__ void conv_unit(LAS unsigned char* lds, const Args& a, int j, int seq0, int c, int tid) {
;     ...
;         f32x4 acc[4][4];
; #pragma unroll
;         for (int gi = 0; gi < 4; ++gi)
; #pragma unroll
;             for (int t = 0; t < 4; ++t) acc[gi][t] = (f32x4){0.f, 0.f, 0.f, 0.f};
;         bf16x8 A0, A1, A2, A3, Bc[4], Bn[4];
;         GATHER(A0, d_lo); GATHER(A1, d_lo + 16); GATHER(A2, d_lo + 32); GATHER(A3, d_lo + 48);
;         int baddr = ub + 2 * (mw - d_lo);
; #pragma unroll
;         for (int gi = 0; gi < 4; ++gi) Bc[gi] = *(const LAS bf16x8*)(lds + baddr + 2 * GS * gi);
.LBB0_1327:
	v_add_u32_e32 v18, s53, v193
	v_add_u32_e32 v24, s63, v193
	ds_read2_b32 v[16:17], v18 offset1:1
	ds_read2_b32 v[20:21], v18 offset0:1 offset1:2
	ds_read2_b32 v[18:19], v18 offset0:3 offset1:4
	ds_read2_b32 v[22:23], v24 offset1:1
	v_add_u32_e32 v25, s72, v193
	ds_read2_b32 v[28:29], v24 offset0:1 offset1:2
	ds_read2_b32 v[30:31], v24 offset0:3 offset1:4
	ds_read2_b32 v[34:35], v25 offset1:1
	ds_read2_b32 v[36:37], v25 offset0:1 offset1:2
	v_add_u32_e32 v24, s73, v193
	ds_read2_b32 v[38:39], v25 offset0:3 offset1:4
	ds_read2_b32 v[40:41], v24 offset1:1
	ds_read2_b32 v[42:43], v24 offset0:1 offset1:2
	ds_read2_b32 v[44:45], v24 offset0:3 offset1:4
	ds_read_b128 v[82:85], v221 offset:8192
	ds_read_b128 v[106:109], v221 offset:8448
	ds_read_b128 v[24:27], v221 offset:8704
	v_mov_b32_e32 v32, v33
	s_waitcnt lgkmcnt(12)
	v_alignbit_b32 v19, v19, v18, v15
	s_waitcnt lgkmcnt(7)
	v_alignbit_b32 v71, v37, v35, v13
	v_alignbit_b32 v70, v36, v34, v12
	v_mov_b32_e32 v34, v33
	v_mov_b32_e32 v35, v33
	v_alignbit_b32 v18, v18, v21, v14
	v_alignbit_b32 v17, v21, v17, v13
	v_alignbit_b32 v16, v20, v16, v12
	v_alignbit_b32 v81, v31, v30, v15
	v_alignbit_b32 v80, v30, v29, v14
	v_alignbit_b32 v79, v29, v23, v13
	v_alignbit_b32 v78, v28, v22, v12
	s_waitcnt lgkmcnt(6)
	v_alignbit_b32 v73, v39, v38, v15
	v_alignbit_b32 v72, v38, v37, v14
	s_waitcnt lgkmcnt(3)
	v_alignbit_b32 v77, v45, v44, v15
	v_alignbit_b32 v76, v44, v43, v14
	v_alignbit_b32 v75, v43, v41, v13
	v_alignbit_b32 v74, v42, v40, v12
	v_mov_b32_e32 v86, 0
	v_mov_b64_e32 v[20:21], v[32:33]
	v_mov_b64_e32 v[50:51], v[34:35]
	v_mov_b64_e32 v[46:47], v[34:35]
	v_mov_b64_e32 v[28:29], v[32:33]
	v_mov_b64_e32 v[42:43], v[34:35]
	v_mov_b64_e32 v[38:39], v[34:35]
	v_mov_b64_e32 v[104:105], v[34:35]
	v_mov_b64_e32 v[100:101], v[34:35]
	s_xor_b64 s[66:67], s[44:45], -1
	s_movk_i32 s56, 0x1020
	s_movk_i32 s71, 0x2100
	v_mov_b32_e32 v134, v200
	v_mov_b32_e32 v135, v199
	v_mov_b32_e32 v136, v197
	v_mov_b32_e32 v137, v196
	v_mov_b64_e32 v[22:23], v[34:35]
	v_mov_b64_e32 v[48:49], v[32:33]
	v_mov_b64_e32 v[44:45], v[32:33]
	v_mov_b64_e32 v[30:31], v[34:35]
	v_mov_b64_e32 v[40:41], v[32:33]
	v_mov_b64_e32 v[36:37], v[32:33]
	v_mov_b64_e32 v[102:103], v[32:33]
	v_mov_b64_e32 v[98:99], v[32:33]
	s_mov_b32 s94, s51
	v_mov_b32_e32 v87, v86
	v_mov_b32_e32 v88, v86
	v_mov_b32_e32 v89, v86
	v_mov_b32_e32 v90, v86
	v_mov_b32_e32 v91, v86
	v_mov_b32_e32 v92, v86
	v_mov_b32_e32 v93, v86
	v_mov_b32_e32 v94, v86
	v_mov_b32_e32 v95, v86
	v_mov_b32_e32 v96, v86
	v_mov_b32_e32 v97, v86
	v_mov_b32_e32 v52, v86
	v_mov_b32_e32 v53, v86
	v_mov_b32_e32 v54, v86
	v_mov_b32_e32 v55, v86

; #define LAS __attribute__((address_space(3)))
; #define GATHER(dst, lagoff) do { unsigned _d[5]; ARAW(_d, lagoff); AFIN(dst, _d); } while (0)
; template <int NQ, int NB, int L>
; __device__ __forceinline__ void conv_unit(LAS unsigned char* lds, const Args& a, int j, int seq0, int c, int tid) {
;     ...
;         f32x4 acc[4][4];
; #pragma unroll
;         for (int gi = 0; gi < 4; ++gi)
; #pragma unroll
;             for (int t = 0; t < 4; ++t) acc[gi][t] = (f32x4){0.f, 0.f, 0.f, 0.f};
;         bf16x8 A0, A1, A2, A3, Bc[4], Bn[4];
;         GATHER(A0, d_lo); GATHER(A1, d_lo + 16); GATHER(A2, d_lo + 32); GATHER(A3, d_lo + 48);
;         int baddr = ub + 2 * (mw - d_lo);
; #pragma unroll
;         for (int gi = 0; gi < 4; ++gi) Bc[gi] = *(const LAS bf16x8*)(lds + baddr + 2 * GS * gi);
.LBB0_1530:
	v_add_u32_e32 v26, s85, v216
	v_add_u32_e32 v32, s93, v216
	ds_read2_b32 v[24:25], v26 offset1:1
	ds_read2_b32 v[28:29], v26 offset0:1 offset1:2
	ds_read2_b32 v[26:27], v26 offset0:3 offset1:4
	ds_read2_b32 v[30:31], v32 offset1:1
	v_add_u32_e32 v36, s94, v216
	ds_read2_b32 v[34:35], v32 offset0:1 offset1:2
	ds_read2_b32 v[40:41], v32 offset0:3 offset1:4
	ds_read2_b32 v[42:43], v36 offset1:1
	ds_read2_b32 v[44:45], v36 offset0:1 offset1:2
	v_add_u32_e32 v32, s95, v216
	ds_read2_b32 v[46:47], v36 offset0:3 offset1:4
	ds_read2_b32 v[48:49], v32 offset1:1
	ds_read2_b32 v[50:51], v32 offset0:1 offset1:2
	ds_read2_b32 v[52:53], v32 offset0:3 offset1:4
	ds_read_b128 v[90:93], v232 offset:16384
	ds_read_b128 v[114:117], v232 offset:16896
	ds_read_b128 v[36:39], v232 offset:17408
	s_waitcnt lgkmcnt(9)
	v_alignbit_b32 v88, v40, v35, v22
	v_alignbit_b32 v87, v35, v31, v21
	v_alignbit_b32 v86, v34, v30, v20
	v_mov_b32_e32 v32, v33
	v_mov_b32_e32 v34, v33
	v_mov_b32_e32 v35, v33
	v_alignbit_b32 v27, v27, v26, v23
	v_alignbit_b32 v26, v26, v29, v22
	v_alignbit_b32 v25, v29, v25, v21
	v_alignbit_b32 v24, v28, v24, v20
	v_alignbit_b32 v89, v41, v40, v23
	s_waitcnt lgkmcnt(6)
	v_alignbit_b32 v81, v47, v46, v23
	v_alignbit_b32 v80, v46, v45, v22
	v_alignbit_b32 v79, v45, v43, v21
	v_alignbit_b32 v78, v44, v42, v20
	s_waitcnt lgkmcnt(3)
	v_alignbit_b32 v85, v53, v52, v23
	v_alignbit_b32 v84, v52, v51, v22
	v_alignbit_b32 v83, v51, v49, v21
	v_alignbit_b32 v82, v50, v48, v20
	v_mov_b32_e32 v98, 0
	v_mov_b64_e32 v[28:29], v[32:33]
	v_mov_b64_e32 v[58:59], v[34:35]
	v_mov_b64_e32 v[54:55], v[34:35]
	v_mov_b64_e32 v[42:43], v[34:35]
	v_mov_b64_e32 v[50:51], v[34:35]
	v_mov_b64_e32 v[46:47], v[34:35]
	v_mov_b64_e32 v[112:113], v[34:35]
	v_mov_b64_e32 v[108:109], v[34:35]
	s_xor_b64 s[72:73], s[74:75], -1
	s_movk_i32 s49, 0x20a0
	s_movk_i32 s56, 0x4200
	v_mov_b32_e32 v142, v223
	v_mov_b32_e32 v143, v222
	v_mov_b32_e32 v144, v220
	v_mov_b32_e32 v145, v219
	v_mov_b64_e32 v[30:31], v[34:35]
	v_mov_b64_e32 v[56:57], v[32:33]
	v_mov_b64_e32 v[52:53], v[32:33]
	v_mov_b64_e32 v[40:41], v[32:33]
	v_mov_b64_e32 v[48:49], v[32:33]
	v_mov_b64_e32 v[44:45], v[32:33]
	v_mov_b64_e32 v[110:111], v[32:33]
	v_mov_b64_e32 v[106:107], v[32:33]
	s_mov_b32 vcc_lo, s53
	v_mov_b32_e32 v99, v98
	v_mov_b32_e32 v100, v98
	v_mov_b32_e32 v101, v98
	v_mov_b32_e32 v94, v98
	v_mov_b32_e32 v95, v98
	v_mov_b32_e32 v96, v98
	v_mov_b32_e32 v97, v98
	v_mov_b32_e32 v102, v98
	v_mov_b32_e32 v103, v98
	v_mov_b32_e32 v104, v98
	v_mov_b32_e32 v105, v98
	v_mov_b32_e32 v60, v98
	v_mov_b32_e32 v61, v98
	v_mov_b32_e32 v62, v98
	v_mov_b32_e32 v63, v98
